# baseline (speedup 1.0000x reference)
; __global__ void __launch_bounds__(NTHREADS, 2) fwd_megakernel(Params p_arg) {
;     ...
;       const int cofs = bcol + wc * 64 + fq * 4;
;       const float* gt = modl + (size_t)(brow >> 12) * 6144 + 2048;
; #pragma unroll
;       for (int n = 0; n < 4; ++n) {
;         const float4 g4 = *(const float4*)(gt + cofs + n * 16);
; #pragma unroll
;         for (int m = 0; m < 8; ++m) {
;           const size_t row = (size_t)brow + wr * 128 + m * 16 + fr;
;           float4 xo = *(const float4*)(xin + row * 1024 + cofs + n * 16);
;           xo.x += g4.x * acc[m][n][0]; xo.y += g4.y * acc[m][n][1]; xo.z += g4.z * acc[m][n][2]; xo.w += g4.w * acc[m][n][3];
;           *(float4*)(pk->out + row * 1024 + cofs + n * 16) = xo;
;         }
;         if (n == 1) __builtin_amdgcn_sched_barrier(0);
;       }
.LBB0_454:
	s_ashr_i32 s0, s47, 4
	v_or_b32_e32 v106, s14, v154
	s_mul_hi_i32 s1, s0, 0x6000
	s_mulk_i32 s0, 0x6000
	s_add_u32 s0, s28, s0
	v_ashrrev_i32_e32 v107, 31, v106
	s_addc_u32 s1, s37, s1
	v_lshlrev_b64 v[106:107], 2, v[106:107]
	v_lshl_add_u64 v[108:109], s[0:1], 0, v[106:107]
	s_mov_b64 s[0:1], 0x7102000
	v_lshl_add_u64 v[140:141], v[108:109], 0, s[0:1]
	s_load_dwordx2 s[0:1], s[4:5], 0x90
	v_lshl_add_u64 v[136:137], v[134:135], 0, s[12:13]
	v_lshl_add_u64 v[144:145], s[10:11], 0, v[106:107]
	v_lshlrev_b64 v[136:137], 12, v[136:137]
	v_lshl_add_u64 v[146:147], v[144:145], 0, v[136:137]
	s_waitcnt lgkmcnt(0)
	v_lshl_add_u64 v[138:139], s[0:1], 0, v[106:107]
	s_mov_b32 s0, 0x7102000
	v_add_co_u32_e32 v106, vcc, s0, v108
	v_lshl_add_u64 v[142:143], v[138:139], 0, v[136:137]
	s_nop 0
	v_addc_co_u32_e32 v107, vcc, 0, v109, vcc
	global_load_dwordx4 v[200:203], v[140:141], off
	global_load_dwordx4 v[204:207], v[140:141], off offset:64
	global_load_dwordx4 v[208:211], v[140:141], off offset:128
	global_load_dwordx4 v[212:215], v[140:141], off offset:192
	v_lshl_add_u64 v[180:181], v[144:145], 0, v[136:137]
	v_or_b32_e32 v196, 0x10000, v136
	v_mov_b32_e32 v197, v137
	v_lshl_add_u64 v[182:183], v[144:145], 0, v[196:197]
	v_or_b32_e32 v196, 0x20000, v136
	v_mov_b32_e32 v197, v137
	v_lshl_add_u64 v[184:185], v[144:145], 0, v[196:197]
	v_or_b32_e32 v196, 0x30000, v136
	v_mov_b32_e32 v197, v137
	v_lshl_add_u64 v[186:187], v[144:145], 0, v[196:197]
	v_or_b32_e32 v196, 0x40000, v136
	v_mov_b32_e32 v197, v137
	v_lshl_add_u64 v[188:189], v[144:145], 0, v[196:197]
	v_or_b32_e32 v196, 0x50000, v136
	v_mov_b32_e32 v197, v137
	v_lshl_add_u64 v[190:191], v[144:145], 0, v[196:197]
	v_or_b32_e32 v196, 0x60000, v136
	v_mov_b32_e32 v197, v137
	v_lshl_add_u64 v[192:193], v[144:145], 0, v[196:197]
	v_or_b32_e32 v196, 0x70000, v136
	v_mov_b32_e32 v197, v137
	v_lshl_add_u64 v[194:195], v[144:145], 0, v[196:197]
	v_sub_co_u32_e32 v198, vcc, v138, v144
	s_nop 1
	v_subb_co_u32_e32 v199, vcc, v139, v145, vcc
	global_load_dwordx4 v[216:219], v[180:181], off
	global_load_dwordx4 v[220:223], v[182:183], off
	global_load_dwordx4 v[224:227], v[184:185], off
	global_load_dwordx4 v[228:231], v[186:187], off
	global_load_dwordx4 v[232:235], v[188:189], off
	global_load_dwordx4 v[236:239], v[190:191], off
	global_load_dwordx4 v[240:243], v[192:193], off
	global_load_dwordx4 v[244:247], v[194:195], off
	global_load_dwordx4 v[248:251], v[180:181], off offset:64
	global_load_dwordx4 v[150:153], v[182:183], off offset:64
	global_load_dwordx4 v[156:159], v[184:185], off offset:64
	global_load_dwordx4 v[172:175], v[186:187], off offset:64
	global_load_dwordx4 v[106:109], v[188:189], off offset:64
	global_load_dwordx4 v[136:139], v[190:191], off offset:64
	global_load_dwordx4 v[144:147], v[192:193], off offset:64
	global_load_dwordx4 v[140:143], v[194:195], off offset:64
	s_waitcnt vmcnt(15)
	v_pk_fma_f32 v[130:131], v[200:201], v[130:131], v[216:217]
	v_pk_fma_f32 v[132:133], v[202:203], v[132:133], v[218:219]
	v_lshl_add_u64 v[196:197], v[180:181], 0, v[198:199]
	global_store_dwordx4 v[196:197], v[130:133], off
	global_load_dwordx4 v[216:219], v[180:181], off offset:128
	s_waitcnt vmcnt(16)
	v_pk_fma_f32 v[126:127], v[200:201], v[126:127], v[220:221]
	v_pk_fma_f32 v[128:129], v[202:203], v[128:129], v[222:223]
	v_lshl_add_u64 v[196:197], v[182:183], 0, v[198:199]
	global_store_dwordx4 v[196:197], v[126:129], off
	global_load_dwordx4 v[220:223], v[182:183], off offset:128
	s_waitcnt vmcnt(17)
	v_pk_fma_f32 v[122:123], v[200:201], v[122:123], v[224:225]
	v_pk_fma_f32 v[124:125], v[202:203], v[124:125], v[226:227]
	v_lshl_add_u64 v[196:197], v[184:185], 0, v[198:199]
	global_store_dwordx4 v[196:197], v[122:125], off
	global_load_dwordx4 v[224:227], v[184:185], off offset:128
	s_waitcnt vmcnt(18)
	v_pk_fma_f32 v[114:115], v[200:201], v[114:115], v[228:229]
	v_pk_fma_f32 v[116:117], v[202:203], v[116:117], v[230:231]
	v_lshl_add_u64 v[196:197], v[186:187], 0, v[198:199]
	global_store_dwordx4 v[196:197], v[114:117], off
	global_load_dwordx4 v[228:231], v[186:187], off offset:128
	s_waitcnt vmcnt(19)
	v_pk_fma_f32 v[118:119], v[200:201], v[118:119], v[232:233]
	v_pk_fma_f32 v[120:121], v[202:203], v[120:121], v[234:235]
	v_lshl_add_u64 v[196:197], v[188:189], 0, v[198:199]
	global_store_dwordx4 v[196:197], v[118:121], off
	global_load_dwordx4 v[232:235], v[188:189], off offset:128
	s_waitcnt vmcnt(20)
	v_pk_fma_f32 v[110:111], v[200:201], v[110:111], v[236:237]
	v_pk_fma_f32 v[112:113], v[202:203], v[112:113], v[238:239]
	v_lshl_add_u64 v[196:197], v[190:191], 0, v[198:199]
	global_store_dwordx4 v[196:197], v[110:113], off
	global_load_dwordx4 v[236:239], v[190:191], off offset:128
	s_waitcnt vmcnt(21)
	v_pk_fma_f32 v[102:103], v[200:201], v[102:103], v[240:241]
	v_pk_fma_f32 v[104:105], v[202:203], v[104:105], v[242:243]
	v_lshl_add_u64 v[196:197], v[192:193], 0, v[198:199]
	global_store_dwordx4 v[196:197], v[102:105], off
	global_load_dwordx4 v[240:243], v[192:193], off offset:128
	s_waitcnt vmcnt(22)
	v_pk_fma_f32 v[98:99], v[200:201], v[98:99], v[244:245]
	v_pk_fma_f32 v[100:101], v[202:203], v[100:101], v[246:247]
	v_lshl_add_u64 v[196:197], v[194:195], 0, v[198:199]
	global_store_dwordx4 v[196:197], v[98:101], off
	global_load_dwordx4 v[244:247], v[194:195], off offset:128
	s_waitcnt vmcnt(23)
	v_pk_fma_f32 v[94:95], v[204:205], v[94:95], v[248:249]
	v_pk_fma_f32 v[96:97], v[206:207], v[96:97], v[250:251]
	v_lshl_add_u64 v[196:197], v[180:181], 0, v[198:199]
	global_store_dwordx4 v[196:197], v[94:97], off offset:64
	global_load_dwordx4 v[248:251], v[180:181], off offset:192
	s_waitcnt vmcnt(24)
; __global__ void __launch_bounds__(NTHREADS, 2) fwd_megakernel(Params p_arg) {
;     ...
; #pragma unroll
;       for (int n = 0; n < 4; ++n) {
;         const float4 g4 = *(const float4*)(gt + cofs + n * 16);
; #pragma unroll
;         for (int m = 0; m < 8; ++m) {
;           const size_t row = (size_t)brow + wr * 128 + m * 16 + fr;
;           float4 xo = *(const float4*)(xin + row * 1024 + cofs + n * 16);
;           xo.x += g4.x * acc[m][n][0]; xo.y += g4.y * acc[m][n][1]; xo.z += g4.z * acc[m][n][2]; xo.w += g4.w * acc[m][n][3];
;           *(float4*)(pk->out + row * 1024 + cofs + n * 16) = xo;
;         }
;         if (n == 1) __builtin_amdgcn_sched_barrier(0);
;       }
;     }
	v_pk_fma_f32 v[90:91], v[204:205], v[90:91], v[150:151]
	v_pk_fma_f32 v[92:93], v[206:207], v[92:93], v[152:153]
	v_lshl_add_u64 v[196:197], v[182:183], 0, v[198:199]
	global_store_dwordx4 v[196:197], v[90:93], off offset:64
	global_load_dwordx4 v[150:153], v[182:183], off offset:192
	s_waitcnt vmcnt(25)
	v_pk_fma_f32 v[86:87], v[204:205], v[86:87], v[156:157]
	v_pk_fma_f32 v[88:89], v[206:207], v[88:89], v[158:159]
	v_lshl_add_u64 v[196:197], v[184:185], 0, v[198:199]
	global_store_dwordx4 v[196:197], v[86:89], off offset:64
	global_load_dwordx4 v[156:159], v[184:185], off offset:192
	s_waitcnt vmcnt(26)
	v_pk_fma_f32 v[78:79], v[204:205], v[78:79], v[172:173]
	v_pk_fma_f32 v[80:81], v[206:207], v[80:81], v[174:175]
	v_lshl_add_u64 v[196:197], v[186:187], 0, v[198:199]
	global_store_dwordx4 v[196:197], v[78:81], off offset:64
	global_load_dwordx4 v[172:175], v[186:187], off offset:192
	s_waitcnt vmcnt(27)
	v_pk_fma_f32 v[82:83], v[204:205], v[82:83], v[106:107]
	v_pk_fma_f32 v[84:85], v[206:207], v[84:85], v[108:109]
	v_lshl_add_u64 v[196:197], v[188:189], 0, v[198:199]
	global_store_dwordx4 v[196:197], v[82:85], off offset:64
	global_load_dwordx4 v[106:109], v[188:189], off offset:192
	s_waitcnt vmcnt(28)
	v_pk_fma_f32 v[74:75], v[204:205], v[74:75], v[136:137]
	v_pk_fma_f32 v[76:77], v[206:207], v[76:77], v[138:139]
	v_lshl_add_u64 v[196:197], v[190:191], 0, v[198:199]
	global_store_dwordx4 v[196:197], v[74:77], off offset:64
	global_load_dwordx4 v[136:139], v[190:191], off offset:192
	s_waitcnt vmcnt(29)
	v_pk_fma_f32 v[70:71], v[204:205], v[70:71], v[144:145]
	v_pk_fma_f32 v[72:73], v[206:207], v[72:73], v[146:147]
	v_lshl_add_u64 v[196:197], v[192:193], 0, v[198:199]
	global_store_dwordx4 v[196:197], v[70:73], off offset:64
	global_load_dwordx4 v[144:147], v[192:193], off offset:192
	s_waitcnt vmcnt(30)
	v_pk_fma_f32 v[66:67], v[204:205], v[66:67], v[140:141]
	v_pk_fma_f32 v[68:69], v[206:207], v[68:69], v[142:143]
	v_lshl_add_u64 v[196:197], v[194:195], 0, v[198:199]
	global_store_dwordx4 v[196:197], v[66:69], off offset:64
	global_load_dwordx4 v[140:143], v[194:195], off offset:192
	s_waitcnt vmcnt(30)
	v_pk_fma_f32 v[62:63], v[208:209], v[62:63], v[216:217]
	v_pk_fma_f32 v[64:65], v[210:211], v[64:65], v[218:219]
	v_lshl_add_u64 v[196:197], v[180:181], 0, v[198:199]
	global_store_dwordx4 v[196:197], v[62:65], off offset:128
	s_waitcnt vmcnt(29)
	v_pk_fma_f32 v[58:59], v[208:209], v[58:59], v[220:221]
	v_pk_fma_f32 v[60:61], v[210:211], v[60:61], v[222:223]
	v_lshl_add_u64 v[196:197], v[182:183], 0, v[198:199]
	global_store_dwordx4 v[196:197], v[58:61], off offset:128
	s_waitcnt vmcnt(28)
	v_pk_fma_f32 v[50:51], v[208:209], v[50:51], v[224:225]
	v_pk_fma_f32 v[52:53], v[210:211], v[52:53], v[226:227]
	v_lshl_add_u64 v[196:197], v[184:185], 0, v[198:199]
	global_store_dwordx4 v[196:197], v[50:53], off offset:128
	s_waitcnt vmcnt(27)
	v_pk_fma_f32 v[42:43], v[208:209], v[42:43], v[228:229]
	v_pk_fma_f32 v[44:45], v[210:211], v[44:45], v[230:231]
	v_lshl_add_u64 v[196:197], v[186:187], 0, v[198:199]
	global_store_dwordx4 v[196:197], v[42:45], off offset:128
	s_waitcnt vmcnt(26)
	v_pk_fma_f32 v[54:55], v[208:209], v[54:55], v[232:233]
	v_pk_fma_f32 v[56:57], v[210:211], v[56:57], v[234:235]
	v_lshl_add_u64 v[196:197], v[188:189], 0, v[198:199]
	global_store_dwordx4 v[196:197], v[54:57], off offset:128
	s_waitcnt vmcnt(25)
	v_pk_fma_f32 v[46:47], v[208:209], v[46:47], v[236:237]
	v_pk_fma_f32 v[48:49], v[210:211], v[48:49], v[238:239]
	v_lshl_add_u64 v[196:197], v[190:191], 0, v[198:199]
	global_store_dwordx4 v[196:197], v[46:49], off offset:128
	s_waitcnt vmcnt(24)
	v_pk_fma_f32 v[38:39], v[208:209], v[38:39], v[240:241]
	v_pk_fma_f32 v[40:41], v[210:211], v[40:41], v[242:243]
	v_lshl_add_u64 v[196:197], v[192:193], 0, v[198:199]
	global_store_dwordx4 v[196:197], v[38:41], off offset:128
	s_waitcnt vmcnt(23)
	v_pk_fma_f32 v[34:35], v[208:209], v[34:35], v[244:245]
	v_pk_fma_f32 v[36:37], v[210:211], v[36:37], v[246:247]
	v_lshl_add_u64 v[196:197], v[194:195], 0, v[198:199]
	global_store_dwordx4 v[196:197], v[34:37], off offset:128
	s_waitcnt vmcnt(22)
	v_pk_fma_f32 v[30:31], v[212:213], v[30:31], v[248:249]
	v_pk_fma_f32 v[32:33], v[214:215], v[32:33], v[250:251]
	v_lshl_add_u64 v[196:197], v[180:181], 0, v[198:199]
	global_store_dwordx4 v[196:197], v[30:33], off offset:192
	s_waitcnt vmcnt(21)
	v_pk_fma_f32 v[26:27], v[212:213], v[26:27], v[150:151]
	v_pk_fma_f32 v[28:29], v[214:215], v[28:29], v[152:153]
	v_lshl_add_u64 v[196:197], v[182:183], 0, v[198:199]
	global_store_dwordx4 v[196:197], v[26:29], off offset:192
	s_waitcnt vmcnt(20)
	v_pk_fma_f32 v[18:19], v[212:213], v[18:19], v[156:157]
	v_pk_fma_f32 v[20:21], v[214:215], v[20:21], v[158:159]
	v_lshl_add_u64 v[196:197], v[184:185], 0, v[198:199]
	global_store_dwordx4 v[196:197], v[18:21], off offset:192
	s_waitcnt vmcnt(19)
	v_pk_fma_f32 v[10:11], v[212:213], v[10:11], v[172:173]
	v_pk_fma_f32 v[12:13], v[214:215], v[12:13], v[174:175]
	v_lshl_add_u64 v[196:197], v[186:187], 0, v[198:199]
	global_store_dwordx4 v[196:197], v[10:13], off offset:192
	s_waitcnt vmcnt(18)
	v_pk_fma_f32 v[22:23], v[212:213], v[22:23], v[106:107]
	v_pk_fma_f32 v[24:25], v[214:215], v[24:25], v[108:109]
	v_lshl_add_u64 v[196:197], v[188:189], 0, v[198:199]
	global_store_dwordx4 v[196:197], v[22:25], off offset:192
	s_waitcnt vmcnt(17)
	v_pk_fma_f32 v[14:15], v[212:213], v[14:15], v[136:137]
	v_pk_fma_f32 v[16:17], v[214:215], v[16:17], v[138:139]
	v_lshl_add_u64 v[196:197], v[190:191], 0, v[198:199]
	global_store_dwordx4 v[196:197], v[14:17], off offset:192
	s_waitcnt vmcnt(16)
	v_pk_fma_f32 v[6:7], v[212:213], v[6:7], v[144:145]
	v_pk_fma_f32 v[8:9], v[214:215], v[8:9], v[146:147]
	v_lshl_add_u64 v[196:197], v[192:193], 0, v[198:199]
	global_store_dwordx4 v[196:197], v[6:9], off offset:192
	s_waitcnt vmcnt(15)
	v_pk_fma_f32 v[2:3], v[212:213], v[2:3], v[140:141]
	v_pk_fma_f32 v[4:5], v[214:215], v[4:5], v[142:143]
	v_lshl_add_u64 v[196:197], v[194:195], 0, v[198:199]
	global_store_dwordx4 v[196:197], v[2:5], off offset:192
	s_mov_b64 s[0:1], 0xc0
	s_mov_b64 s[52:53], 0xc0
	s_add_i32 s44, s44, 1
	s_mov_b64 s[98:99], s[54:55]
	s_mov_b64 s[0:1], 0

; __global__ void __launch_bounds__(NTHREADS, 2) fwd_megakernel(Params p_arg) {
;     ...
;       const int cofs = bcol + wc * 64 + fq * 4;
;       const float* gt = modl + (size_t)(brow >> 12) * 6144 + 5120;
; #pragma unroll
;       for (int n = 0; n < 4; ++n) {
;         const float4 g4 = *(const float4*)(gt + cofs + n * 16);
; #pragma unroll
;         for (int m = 0; m < 8; ++m) {
;           const size_t row = (size_t)brow + wr * 128 + m * 16 + fr;
;           float4 xo = *(const float4*)(pk->out + row * 1024 + cofs + n * 16);
;           xo.x += g4.x * acc[m][n][0]; xo.y += g4.y * acc[m][n][1]; xo.z += g4.z * acc[m][n][2]; xo.w += g4.w * acc[m][n][3];
;           *(float4*)(pk->out + row * 1024 + cofs + n * 16) = xo;
;         }
;         if (n == 1) __builtin_amdgcn_sched_barrier(0);
;       }
.LBB0_670:
	s_ashr_i32 s0, s20, 4
	v_or_b32_e32 v132, s21, v144
	s_mul_hi_i32 s1, s0, 0x6000
	s_mulk_i32 s0, 0x6000
	s_add_u32 s0, s12, s0
	v_ashrrev_i32_e32 v133, 31, v132
	s_addc_u32 s1, s13, s1
	v_lshlrev_b64 v[132:133], 2, v[132:133]
	v_lshl_add_u64 v[146:147], s[0:1], 0, v[132:133]
	s_mov_b64 s[0:1], 0x7105000
	v_lshl_add_u64 v[134:135], v[146:147], 0, s[0:1]
	s_load_dwordx2 s[0:1], s[4:5], 0x90
	v_lshl_add_u64 v[136:137], v[130:131], 0, s[6:7]
	s_waitcnt lgkmcnt(0)
	v_lshl_add_u64 v[138:139], s[0:1], 0, v[132:133]
	s_mov_b32 s0, 0x7105000
	v_add_co_u32_e32 v146, vcc, s0, v146
	v_lshlrev_b64 v[132:133], 12, v[136:137]
	s_nop 0
	v_addc_co_u32_e32 v147, vcc, 0, v147, vcc
	v_lshl_add_u64 v[136:137], v[138:139], 0, v[132:133]
	global_load_dwordx4 v[200:203], v[134:135], off
	global_load_dwordx4 v[204:207], v[134:135], off offset:64
	global_load_dwordx4 v[208:211], v[134:135], off offset:128
	global_load_dwordx4 v[212:215], v[134:135], off offset:192
	v_lshl_add_u64 v[180:181], v[138:139], 0, v[132:133]
	v_or_b32_e32 v196, 0x10000, v132
	v_mov_b32_e32 v197, v133
	v_lshl_add_u64 v[182:183], v[138:139], 0, v[196:197]
	v_or_b32_e32 v196, 0x20000, v132
	v_mov_b32_e32 v197, v133
	v_lshl_add_u64 v[184:185], v[138:139], 0, v[196:197]
	v_or_b32_e32 v196, 0x30000, v132
	v_mov_b32_e32 v197, v133
	v_lshl_add_u64 v[186:187], v[138:139], 0, v[196:197]
	v_or_b32_e32 v196, 0x40000, v132
	v_mov_b32_e32 v197, v133
	v_lshl_add_u64 v[188:189], v[138:139], 0, v[196:197]
	v_or_b32_e32 v196, 0x50000, v132
	v_mov_b32_e32 v197, v133
	v_lshl_add_u64 v[190:191], v[138:139], 0, v[196:197]
	v_or_b32_e32 v196, 0x60000, v132
	v_mov_b32_e32 v197, v133
	v_lshl_add_u64 v[192:193], v[138:139], 0, v[196:197]
	v_or_b32_e32 v196, 0x70000, v132
	v_mov_b32_e32 v197, v133
	v_lshl_add_u64 v[194:195], v[138:139], 0, v[196:197]
	global_load_dwordx4 v[216:219], v[180:181], off
	global_load_dwordx4 v[220:223], v[182:183], off
	global_load_dwordx4 v[224:227], v[184:185], off
	global_load_dwordx4 v[228:231], v[186:187], off
	global_load_dwordx4 v[232:235], v[188:189], off
	global_load_dwordx4 v[236:239], v[190:191], off
	global_load_dwordx4 v[240:243], v[192:193], off
	global_load_dwordx4 v[244:247], v[194:195], off
	global_load_dwordx4 v[248:251], v[180:181], off offset:64
	global_load_dwordx4 v[150:153], v[182:183], off offset:64
	global_load_dwordx4 v[154:157], v[184:185], off offset:64
	global_load_dwordx4 v[158:161], v[186:187], off offset:64
	global_load_dwordx4 v[172:175], v[188:189], off offset:64
	global_load_dwordx4 v[132:135], v[190:191], off offset:64
	global_load_dwordx4 v[136:139], v[192:193], off offset:64
	global_load_dwordx4 v[196:199], v[194:195], off offset:64
	s_waitcnt vmcnt(15)
	v_pk_fma_f32 v[126:127], v[200:201], v[126:127], v[216:217]
	v_pk_fma_f32 v[128:129], v[202:203], v[128:129], v[218:219]
	global_store_dwordx4 v[180:181], v[126:129], off
	global_load_dwordx4 v[216:219], v[180:181], off offset:128
	s_waitcnt vmcnt(16)
	v_pk_fma_f32 v[122:123], v[200:201], v[122:123], v[220:221]
	v_pk_fma_f32 v[124:125], v[202:203], v[124:125], v[222:223]
	global_store_dwordx4 v[182:183], v[122:125], off
	global_load_dwordx4 v[220:223], v[182:183], off offset:128
	s_waitcnt vmcnt(17)
	v_pk_fma_f32 v[118:119], v[200:201], v[118:119], v[224:225]
	v_pk_fma_f32 v[120:121], v[202:203], v[120:121], v[226:227]
	global_store_dwordx4 v[184:185], v[118:121], off
	global_load_dwordx4 v[224:227], v[184:185], off offset:128
	s_waitcnt vmcnt(18)
	v_pk_fma_f32 v[110:111], v[200:201], v[110:111], v[228:229]
	v_pk_fma_f32 v[112:113], v[202:203], v[112:113], v[230:231]
	global_store_dwordx4 v[186:187], v[110:113], off
	global_load_dwordx4 v[228:231], v[186:187], off offset:128
	s_waitcnt vmcnt(19)
	v_pk_fma_f32 v[114:115], v[200:201], v[114:115], v[232:233]
	v_pk_fma_f32 v[116:117], v[202:203], v[116:117], v[234:235]
	global_store_dwordx4 v[188:189], v[114:117], off
	global_load_dwordx4 v[232:235], v[188:189], off offset:128
	s_waitcnt vmcnt(20)
	v_pk_fma_f32 v[106:107], v[200:201], v[106:107], v[236:237]
	v_pk_fma_f32 v[108:109], v[202:203], v[108:109], v[238:239]
	global_store_dwordx4 v[190:191], v[106:109], off
	global_load_dwordx4 v[236:239], v[190:191], off offset:128
	s_waitcnt vmcnt(21)
	v_pk_fma_f32 v[102:103], v[200:201], v[102:103], v[240:241]
	v_pk_fma_f32 v[104:105], v[202:203], v[104:105], v[242:243]
	global_store_dwordx4 v[192:193], v[102:105], off
	global_load_dwordx4 v[240:243], v[192:193], off offset:128
	s_waitcnt vmcnt(22)
	v_pk_fma_f32 v[98:99], v[200:201], v[98:99], v[244:245]
	v_pk_fma_f32 v[100:101], v[202:203], v[100:101], v[246:247]
	global_store_dwordx4 v[194:195], v[98:101], off
	global_load_dwordx4 v[244:247], v[194:195], off offset:128
	s_waitcnt vmcnt(23)
	v_pk_fma_f32 v[86:87], v[204:205], v[86:87], v[248:249]
	v_pk_fma_f32 v[88:89], v[206:207], v[88:89], v[250:251]
	global_store_dwordx4 v[180:181], v[86:89], off offset:64
	global_load_dwordx4 v[248:251], v[180:181], off offset:192
	s_waitcnt vmcnt(24)
; __global__ void __launch_bounds__(NTHREADS, 2) fwd_megakernel(Params p_arg) {
;     ...
; #pragma unroll
;       for (int n = 0; n < 4; ++n) {
;         const float4 g4 = *(const float4*)(gt + cofs + n * 16);
; #pragma unroll
;         for (int m = 0; m < 8; ++m) {
;           const size_t row = (size_t)brow + wr * 128 + m * 16 + fr;
;           float4 xo = *(const float4*)(pk->out + row * 1024 + cofs + n * 16);
;           xo.x += g4.x * acc[m][n][0]; xo.y += g4.y * acc[m][n][1]; xo.z += g4.z * acc[m][n][2]; xo.w += g4.w * acc[m][n][3];
;           *(float4*)(pk->out + row * 1024 + cofs + n * 16) = xo;
;         }
;         if (n == 1) __builtin_amdgcn_sched_barrier(0);
;       }
;     }
	v_pk_fma_f32 v[90:91], v[204:205], v[90:91], v[150:151]
	v_pk_fma_f32 v[92:93], v[206:207], v[92:93], v[152:153]
	global_store_dwordx4 v[182:183], v[90:93], off offset:64
	global_load_dwordx4 v[150:153], v[182:183], off offset:192
	s_waitcnt vmcnt(25)
	v_pk_fma_f32 v[94:95], v[204:205], v[94:95], v[154:155]
	v_pk_fma_f32 v[96:97], v[206:207], v[96:97], v[156:157]
	global_store_dwordx4 v[184:185], v[94:97], off offset:64
	global_load_dwordx4 v[154:157], v[184:185], off offset:192
	s_waitcnt vmcnt(26)
	v_pk_fma_f32 v[82:83], v[204:205], v[82:83], v[158:159]
	v_pk_fma_f32 v[84:85], v[206:207], v[84:85], v[160:161]
	global_store_dwordx4 v[186:187], v[82:85], off offset:64
	global_load_dwordx4 v[158:161], v[186:187], off offset:192
	s_waitcnt vmcnt(27)
	v_pk_fma_f32 v[78:79], v[204:205], v[78:79], v[172:173]
	v_pk_fma_f32 v[80:81], v[206:207], v[80:81], v[174:175]
	global_store_dwordx4 v[188:189], v[78:81], off offset:64
	global_load_dwordx4 v[172:175], v[188:189], off offset:192
	s_waitcnt vmcnt(28)
	v_pk_fma_f32 v[74:75], v[204:205], v[74:75], v[132:133]
	v_pk_fma_f32 v[76:77], v[206:207], v[76:77], v[134:135]
	global_store_dwordx4 v[190:191], v[74:77], off offset:64
	global_load_dwordx4 v[132:135], v[190:191], off offset:192
	s_waitcnt vmcnt(29)
	v_pk_fma_f32 v[70:71], v[204:205], v[70:71], v[136:137]
	v_pk_fma_f32 v[72:73], v[206:207], v[72:73], v[138:139]
	global_store_dwordx4 v[192:193], v[70:73], off offset:64
	global_load_dwordx4 v[136:139], v[192:193], off offset:192
	s_waitcnt vmcnt(30)
	v_pk_fma_f32 v[66:67], v[204:205], v[66:67], v[196:197]
	v_pk_fma_f32 v[68:69], v[206:207], v[68:69], v[198:199]
	global_store_dwordx4 v[194:195], v[66:69], off offset:64
	global_load_dwordx4 v[196:199], v[194:195], off offset:192
	s_waitcnt vmcnt(30)
	v_pk_fma_f32 v[62:63], v[208:209], v[62:63], v[216:217]
	v_pk_fma_f32 v[64:65], v[210:211], v[64:65], v[218:219]
	global_store_dwordx4 v[180:181], v[62:65], off offset:128
	s_waitcnt vmcnt(29)
	v_pk_fma_f32 v[58:59], v[208:209], v[58:59], v[220:221]
	v_pk_fma_f32 v[60:61], v[210:211], v[60:61], v[222:223]
	global_store_dwordx4 v[182:183], v[58:61], off offset:128
	s_waitcnt vmcnt(28)
	v_pk_fma_f32 v[54:55], v[208:209], v[54:55], v[224:225]
	v_pk_fma_f32 v[56:57], v[210:211], v[56:57], v[226:227]
	global_store_dwordx4 v[184:185], v[54:57], off offset:128
	s_waitcnt vmcnt(27)
	v_pk_fma_f32 v[46:47], v[208:209], v[46:47], v[228:229]
	v_pk_fma_f32 v[48:49], v[210:211], v[48:49], v[230:231]
	global_store_dwordx4 v[186:187], v[46:49], off offset:128
	s_waitcnt vmcnt(26)
	v_pk_fma_f32 v[50:51], v[208:209], v[50:51], v[232:233]
	v_pk_fma_f32 v[52:53], v[210:211], v[52:53], v[234:235]
	global_store_dwordx4 v[188:189], v[50:53], off offset:128
	s_waitcnt vmcnt(25)
	v_pk_fma_f32 v[42:43], v[208:209], v[42:43], v[236:237]
	v_pk_fma_f32 v[44:45], v[210:211], v[44:45], v[238:239]
	global_store_dwordx4 v[190:191], v[42:45], off offset:128
	s_waitcnt vmcnt(24)
	v_pk_fma_f32 v[38:39], v[208:209], v[38:39], v[240:241]
	v_pk_fma_f32 v[40:41], v[210:211], v[40:41], v[242:243]
	global_store_dwordx4 v[192:193], v[38:41], off offset:128
	s_waitcnt vmcnt(23)
	v_pk_fma_f32 v[34:35], v[208:209], v[34:35], v[244:245]
	v_pk_fma_f32 v[36:37], v[210:211], v[36:37], v[246:247]
	global_store_dwordx4 v[194:195], v[34:37], off offset:128
	s_waitcnt vmcnt(22)
	v_pk_fma_f32 v[22:23], v[212:213], v[22:23], v[248:249]
	v_pk_fma_f32 v[24:25], v[214:215], v[24:25], v[250:251]
	global_store_dwordx4 v[180:181], v[22:25], off offset:192
	s_waitcnt vmcnt(21)
	v_pk_fma_f32 v[26:27], v[212:213], v[26:27], v[150:151]
	v_pk_fma_f32 v[28:29], v[214:215], v[28:29], v[152:153]
	global_store_dwordx4 v[182:183], v[26:29], off offset:192
	s_waitcnt vmcnt(20)
	v_pk_fma_f32 v[30:31], v[212:213], v[30:31], v[154:155]
	v_pk_fma_f32 v[32:33], v[214:215], v[32:33], v[156:157]
	global_store_dwordx4 v[184:185], v[30:33], off offset:192
	s_waitcnt vmcnt(19)
	v_pk_fma_f32 v[18:19], v[212:213], v[18:19], v[158:159]
	v_pk_fma_f32 v[20:21], v[214:215], v[20:21], v[160:161]
	global_store_dwordx4 v[186:187], v[18:21], off offset:192
	s_waitcnt vmcnt(18)
	v_pk_fma_f32 v[14:15], v[212:213], v[14:15], v[172:173]
	v_pk_fma_f32 v[16:17], v[214:215], v[16:17], v[174:175]
	global_store_dwordx4 v[188:189], v[14:17], off offset:192
	s_waitcnt vmcnt(17)
	v_pk_fma_f32 v[10:11], v[212:213], v[10:11], v[132:133]
	v_pk_fma_f32 v[12:13], v[214:215], v[12:13], v[134:135]
	global_store_dwordx4 v[190:191], v[10:13], off offset:192
	s_waitcnt vmcnt(16)
	v_pk_fma_f32 v[6:7], v[212:213], v[6:7], v[136:137]
	v_pk_fma_f32 v[8:9], v[214:215], v[8:9], v[138:139]
	global_store_dwordx4 v[192:193], v[6:9], off offset:192
	s_waitcnt vmcnt(15)
	v_pk_fma_f32 v[2:3], v[212:213], v[2:3], v[196:197]
	v_pk_fma_f32 v[4:5], v[214:215], v[4:5], v[198:199]
	global_store_dwordx4 v[194:195], v[2:5], off offset:192
	s_add_i32 s19, s19, 1
	s_mov_b64 s[0:1], 0
